# up-GEMM loop: LDS-DMA pieces use SGPR base + 32-bit lane offset instead of a 64-bit VALU add per piece (plus 192-row loop change)
# speedup vs baseline: 1.0024x; 1.0024x over previous
; #define PG8_STAGE(bufoff, gbase, voff) do { _Pragma("unroll") for (int _i = 0; _i < 2; ++_i) \
;         __builtin_amdgcn_global_load_lds((const unsigned*)((const char*)(gbase) + (voff)[_i]), (LAS unsigned*)(lds + (bufoff) + ldsw + _i * 8192), 16, 0, 0); } while (0)
; #define PG8_LDA(dst, b, h) do { _Pragma("unroll") for (int m = 0; m < NM; ++m) _Pragma("unroll") for (int k = 0; k < 2; ++k) dst[m][k] = *(const LAS bf16x8*)(lds + PG8_SA(b, h) + aoff + m * 2048 + k * 1024); } while (0)
; #define PG8_LDB(dst, b, h) do { _Pragma("unroll") for (int n = 0; n < 2; ++n) _Pragma("unroll") for (int k = 0; k < 2; ++k) dst[n][k] = *(const LAS bf16x8*)(lds + PG8_SB(b, h) + boff + n * 2048 + k * 1024); } while (0)
; #define PG8_MMA(ai, bj, At, Bt) do { __builtin_amdgcn_s_setprio(1); _Pragma("unroll") for (int m = 0; m < NM; ++m) _Pragma("unroll") for (int n = 0; n < 2; ++n) _Pragma("unroll") for (int k = 0; k < 2; ++k) \
;         acc[ai][bj][m][n] = __builtin_amdgcn_mfma_f32_16x16x32_bf16(Bt[n][k], At[m][k], acc[ai][bj][m][n], 0, 0, 0); __builtin_amdgcn_s_setprio(0); } while (0)
; #define PG8_WAIT_V(n) asm volatile("s_waitcnt vmcnt(" #n ")" ::: "memory")
; #define PG8_WAIT_L(n) asm volatile("s_waitcnt lgkmcnt(" #n ")" ::: "memory")
; #define PG8_BAR __builtin_amdgcn_s_barrier()
; #define PG8_SCHED __builtin_amdgcn_sched_barrier(0)
;     ...
;         for (int t = 0; t < nt; t += 2) {
;             const bool last = (t == nt - 2);
;             const char* a1 = cA + (size_t)(t + 1) * kstep;
;             const char* a2 = last ? nA : cA + (size_t)(t + 2) * kstep; const char* b2 = last ? nB : cB + (size_t)(t + 2) * kstep;
;             const char* a3 = a2 + kstep; const char* b3 = b2 + kstep;
;             if constexpr (SP2) {
;             PG8_LDB(B0, 0, 0); PG8_LDB(B1, 0, 1); PG8_SCHED; PG8_LDA(At, 0, 0); PG8_STAGE(PG8_SA(1, 1), a1 + hstepA, voffA);
;             PG8_WAIT_V(8); PG8_WAIT_L(0); PG8_BAR; PG8_MMA(0, 0, At, B0); PG8_MMA(0, 1, At, B1); PG8_BAR; PG8_SCHED;
;             PG8_LDA(At, 0, 1); PG8_STAGE(PG8_SB(0, 0), b2, voffB); PG8_STAGE(PG8_SB(0, 1), b2 + hstepB, voffB); PG8_STAGE(PG8_SA(0, 0), a2, voffA);
;             PG8_WAIT_V(8); PG8_WAIT_L(0); PG8_BAR; PG8_MMA(1, 0, At, B0); PG8_MMA(1, 1, At, B1); PG8_BAR; PG8_SCHED;
.LBB0_1783:
	v_add_u32_e32 v0, s64, v208
	ds_read_b128 v[130:133], v0
	ds_read_b128 v[134:137], v0 offset:1024
	ds_read_b128 v[138:141], v0 offset:2048
	ds_read_b128 v[142:145], v0 offset:3072
	v_add_u32_e32 v0, s70, v208
	ds_read_b128 v[146:149], v0
	ds_read_b128 v[150:153], v0 offset:1024
	ds_read_b128 v[154:157], v0 offset:2048
	ds_read_b128 v[158:161], v0 offset:3072
	s_add_u32 s14, s12, 0xfff80080
	s_addc_u32 s15, s13, -1
	s_cmp_eq_u32 vcc_lo, 28
	s_cselect_b32 s47, s2, s15
	s_cselect_b32 s46, s3, s14
	s_cselect_b32 s15, s9, s41
	s_cselect_b32 s14, s11, s37
	s_add_i32 m0, s73, 0xc000
	ds_read_b128 v[162:165], v209
	ds_read_b128 v[166:169], v209 offset:1024
	ds_read_b128 v[170:173], v209 offset:2048
	ds_read_b128 v[174:177], v209 offset:3072
	ds_read_b128 v[190:193], v209 offset:4096
	ds_read_b128 v[194:197], v209 offset:5120
	ds_read_b128 v[198:201], v209 offset:6144
	ds_read_b128 v[202:205], v209 offset:7168
	global_load_lds_dwordx4 v186, s[12:13]
	s_add_i32 m0, s73, 0xe000
	s_nop 0
	global_load_lds_dwordx4 v188, s[12:13]
	s_waitcnt vmcnt(8)
	s_waitcnt lgkmcnt(0)
	s_barrier
	s_setprio 1
	s_waitcnt lgkmcnt(0)
	v_mfma_f32_16x16x32_bf16 v[126:129], v[130:133], v[162:165], v[126:129]
	v_mfma_f32_16x16x32_bf16 v[94:97], v[138:141], v[162:165], v[94:97]
	v_mfma_f32_16x16x32_bf16 v[110:113], v[130:133], v[170:173], v[110:113]
	v_mfma_f32_16x16x32_bf16 v[70:73], v[138:141], v[170:173], v[70:73]
	v_mfma_f32_16x16x32_bf16 v[106:109], v[130:133], v[190:193], v[106:109]
	v_mfma_f32_16x16x32_bf16 v[66:69], v[138:141], v[190:193], v[66:69]
	v_mfma_f32_16x16x32_bf16 v[118:121], v[130:133], v[198:201], v[118:121]
	v_mfma_f32_16x16x32_bf16 v[86:89], v[138:141], v[198:201], v[86:89]
	v_mfma_f32_16x16x32_bf16 v[126:129], v[134:137], v[166:169], v[126:129]
	v_mfma_f32_16x16x32_bf16 v[94:97], v[142:145], v[166:169], v[94:97]
	v_mfma_f32_16x16x32_bf16 v[110:113], v[134:137], v[174:177], v[110:113]
	v_mfma_f32_16x16x32_bf16 v[70:73], v[142:145], v[174:177], v[70:73]
	v_mfma_f32_16x16x32_bf16 v[106:109], v[134:137], v[194:197], v[106:109]
	v_mfma_f32_16x16x32_bf16 v[66:69], v[142:145], v[194:197], v[66:69]
	v_mfma_f32_16x16x32_bf16 v[118:121], v[134:137], v[202:205], v[118:121]
	v_mfma_f32_16x16x32_bf16 v[86:89], v[142:145], v[202:205], v[86:89]
	s_setprio 0
	s_setprio 1
	v_mfma_f32_16x16x32_bf16 v[122:125], v[146:149], v[162:165], v[122:125]
	v_mfma_f32_16x16x32_bf16 v[90:93], v[154:157], v[162:165], v[90:93]
	v_mfma_f32_16x16x32_bf16 v[102:105], v[146:149], v[170:173], v[102:105]
	v_mfma_f32_16x16x32_bf16 v[62:65], v[154:157], v[170:173], v[62:65]
	v_mfma_f32_16x16x32_bf16 v[98:101], v[146:149], v[190:193], v[98:101]
	v_mfma_f32_16x16x32_bf16 v[58:61], v[154:157], v[190:193], v[58:61]
	v_mfma_f32_16x16x32_bf16 v[114:117], v[146:149], v[198:201], v[114:117]
	v_mfma_f32_16x16x32_bf16 v[82:85], v[154:157], v[198:201], v[82:85]
	v_mfma_f32_16x16x32_bf16 v[122:125], v[150:153], v[166:169], v[122:125]
	v_mfma_f32_16x16x32_bf16 v[90:93], v[158:161], v[166:169], v[90:93]
	v_mfma_f32_16x16x32_bf16 v[102:105], v[150:153], v[174:177], v[102:105]
	v_mfma_f32_16x16x32_bf16 v[62:65], v[158:161], v[174:177], v[62:65]
	v_mfma_f32_16x16x32_bf16 v[98:101], v[150:153], v[194:197], v[98:101]
	v_mfma_f32_16x16x32_bf16 v[58:61], v[158:161], v[194:197], v[58:61]
	v_mfma_f32_16x16x32_bf16 v[114:117], v[150:153], v[202:205], v[114:117]
	v_mfma_f32_16x16x32_bf16 v[82:85], v[158:161], v[202:205], v[82:85]
	s_setprio 0
	s_barrier
	s_mov_b32 m0, s68
	s_add_u32 s22, s14, 0x80000
	ds_read_b128 v[162:165], v209 offset:16384
	ds_read_b128 v[166:169], v209 offset:17408
	ds_read_b128 v[170:173], v209 offset:18432
	ds_read_b128 v[174:177], v209 offset:19456
	ds_read_b128 v[190:193], v209 offset:20480
	ds_read_b128 v[194:197], v209 offset:21504
	ds_read_b128 v[198:201], v209 offset:22528
	ds_read_b128 v[202:205], v209 offset:23552
	global_load_lds_dwordx4 v180, s[14:15]
	s_mov_b32 m0, s69
	s_addc_u32 s23, s15, 0
	global_load_lds_dwordx4 v184, s[14:15]
	s_mov_b32 m0, s71
	s_nop 0
	global_load_lds_dwordx4 v180, s[22:23]
	s_mov_b32 m0, s72
	s_nop 0
	global_load_lds_dwordx4 v184, s[22:23]
	s_mov_b32 m0, s73
	s_nop 0
	global_load_lds_dwordx4 v178, s[46:47]
	s_mov_b32 m0, s74
	s_nop 0
	global_load_lds_dwordx4 v182, s[46:47]
	s_waitcnt vmcnt(8)
	s_waitcnt lgkmcnt(0)
	s_barrier
	s_setprio 1
	s_waitcnt lgkmcnt(0)
	v_mfma_f32_16x16x32_bf16 v[46:49], v[130:133], v[162:165], v[46:49]
	v_mfma_f32_16x16x32_bf16 v[22:25], v[138:141], v[162:165], v[22:25]
	v_mfma_f32_16x16x32_bf16 v[42:45], v[130:133], v[170:173], v[42:45]
	v_mfma_f32_16x16x32_bf16 v[18:21], v[138:141], v[170:173], v[18:21]
	v_mfma_f32_16x16x32_bf16 v[38:41], v[130:133], v[190:193], v[38:41]
	v_mfma_f32_16x16x32_bf16 v[14:17], v[138:141], v[190:193], v[14:17]
	v_mfma_f32_16x16x32_bf16 v[78:81], v[130:133], v[198:201], v[78:81]
	v_mfma_f32_16x16x32_bf16 v[54:57], v[138:141], v[198:201], v[54:57]
	v_mfma_f32_16x16x32_bf16 v[46:49], v[134:137], v[166:169], v[46:49]
	v_mfma_f32_16x16x32_bf16 v[22:25], v[142:145], v[166:169], v[22:25]
	v_mfma_f32_16x16x32_bf16 v[42:45], v[134:137], v[174:177], v[42:45]
	v_mfma_f32_16x16x32_bf16 v[18:21], v[142:145], v[174:177], v[18:21]
	v_mfma_f32_16x16x32_bf16 v[38:41], v[134:137], v[194:197], v[38:41]
	v_mfma_f32_16x16x32_bf16 v[14:17], v[142:145], v[194:197], v[14:17]
	v_mfma_f32_16x16x32_bf16 v[78:81], v[134:137], v[202:205], v[78:81]
	v_mfma_f32_16x16x32_bf16 v[54:57], v[142:145], v[202:205], v[54:57]
	s_setprio 0
	s_setprio 1
	v_mfma_f32_16x16x32_bf16 v[34:37], v[146:149], v[162:165], v[34:37]
	v_mfma_f32_16x16x32_bf16 v[10:13], v[154:157], v[162:165], v[10:13]
	v_mfma_f32_16x16x32_bf16 v[30:33], v[146:149], v[170:173], v[30:33]
	v_mfma_f32_16x16x32_bf16 v[6:9], v[154:157], v[170:173], v[6:9]
	v_mfma_f32_16x16x32_bf16 v[26:29], v[146:149], v[190:193], v[26:29]
	v_mfma_f32_16x16x32_bf16 v[2:5], v[154:157], v[190:193], v[2:5]
	v_mfma_f32_16x16x32_bf16 v[74:77], v[146:149], v[198:201], v[74:77]
	v_mfma_f32_16x16x32_bf16 v[50:53], v[154:157], v[198:201], v[50:53]
	v_mfma_f32_16x16x32_bf16 v[34:37], v[150:153], v[166:169], v[34:37]
	v_mfma_f32_16x16x32_bf16 v[10:13], v[158:161], v[166:169], v[10:13]
	v_mfma_f32_16x16x32_bf16 v[30:33], v[150:153], v[174:177], v[30:33]
	v_mfma_f32_16x16x32_bf16 v[6:9], v[158:161], v[174:177], v[6:9]
	v_mfma_f32_16x16x32_bf16 v[26:29], v[150:153], v[194:197], v[26:29]
	v_mfma_f32_16x16x32_bf16 v[2:5], v[158:161], v[194:197], v[2:5]
	v_mfma_f32_16x16x32_bf16 v[74:77], v[150:153], v[202:205], v[74:77]
	v_mfma_f32_16x16x32_bf16 v[50:53], v[158:161], v[202:205], v[50:53]
	s_setprio 0
	s_barrier
; #define PG8_STAGE(bufoff, gbase, voff) do { _Pragma("unroll") for (int _i = 0; _i < 2; ++_i) \
;         __builtin_amdgcn_global_load_lds((const unsigned*)((const char*)(gbase) + (voff)[_i]), (LAS unsigned*)(lds + (bufoff) + ldsw + _i * 8192), 16, 0, 0); } while (0)
; #define PG8_LDA(dst, b, h) do { _Pragma("unroll") for (int m = 0; m < NM; ++m) _Pragma("unroll") for (int k = 0; k < 2; ++k) dst[m][k] = *(const LAS bf16x8*)(lds + PG8_SA(b, h) + aoff + m * 2048 + k * 1024); } while (0)
; #define PG8_LDB(dst, b, h) do { _Pragma("unroll") for (int n = 0; n < 2; ++n) _Pragma("unroll") for (int k = 0; k < 2; ++k) dst[n][k] = *(const LAS bf16x8*)(lds + PG8_SB(b, h) + boff + n * 2048 + k * 1024); } while (0)
; #define PG8_MMA(ai, bj, At, Bt) do { __builtin_amdgcn_s_setprio(1); _Pragma("unroll") for (int m = 0; m < NM; ++m) _Pragma("unroll") for (int n = 0; n < 2; ++n) _Pragma("unroll") for (int k = 0; k < 2; ++k) \
;         acc[ai][bj][m][n] = __builtin_amdgcn_mfma_f32_16x16x32_bf16(Bt[n][k], At[m][k], acc[ai][bj][m][n], 0, 0, 0); __builtin_amdgcn_s_setprio(0); } while (0)
; #define PG8_WAIT_V(n) asm volatile("s_waitcnt vmcnt(" #n ")" ::: "memory")
; #define PG8_WAIT_L(n) asm volatile("s_waitcnt lgkmcnt(" #n ")" ::: "memory")
; #define PG8_BAR __builtin_amdgcn_s_barrier()
; #define PG8_SCHED __builtin_amdgcn_sched_barrier(0)
;     ...
;             PG8_LDB(B0, 1, 0); PG8_LDB(B1, 1, 1); PG8_SCHED; PG8_LDA(At, 1, 0); PG8_STAGE(PG8_SA(0, 1), a2 + hstepA, voffA);
;             PG8_WAIT_V(8); PG8_WAIT_L(0); PG8_BAR; PG8_MMA(0, 0, At, B0); PG8_MMA(0, 1, At, B1); PG8_BAR; PG8_SCHED;
;             PG8_LDA(At, 1, 1); PG8_STAGE(PG8_SB(1, 0), b3, voffB); PG8_STAGE(PG8_SB(1, 1), b3 + hstepB, voffB); PG8_STAGE(PG8_SA(1, 0), a3, voffA);
;             PG8_WAIT_V(8); PG8_WAIT_L(0); PG8_BAR; PG8_MMA(1, 0, At, B0); PG8_MMA(1, 1, At, B1); PG8_BAR; PG8_SCHED;
	v_add_u32_e32 v0, s94, v208
	ds_read_b128 v[130:133], v0
	ds_read_b128 v[134:137], v0 offset:1024
	ds_read_b128 v[138:141], v0 offset:2048
	ds_read_b128 v[142:145], v0 offset:3072
	v_add_u32_e32 v0, s62, v208
	ds_read_b128 v[146:149], v0
	ds_read_b128 v[150:153], v0 offset:1024
	ds_read_b128 v[154:157], v0 offset:2048
	ds_read_b128 v[158:161], v0 offset:3072
	s_add_u32 s22, s46, 0x80000
	s_addc_u32 s23, s47, 0
	s_mov_b32 m0, s75
	ds_read_b128 v[162:165], v209 offset:32768
	ds_read_b128 v[166:169], v209 offset:33792
	ds_read_b128 v[170:173], v209 offset:34816
	ds_read_b128 v[174:177], v209 offset:35840
	ds_read_b128 v[190:193], v209 offset:36864
	ds_read_b128 v[194:197], v209 offset:37888
	ds_read_b128 v[198:201], v209 offset:38912
	ds_read_b128 v[202:205], v209 offset:39936
	global_load_lds_dwordx4 v178, s[22:23]
	s_mov_b32 m0, s80
	s_nop 0
	global_load_lds_dwordx4 v182, s[22:23]
	s_waitcnt vmcnt(8)
	s_waitcnt lgkmcnt(0)
	s_barrier
	s_setprio 1
	s_waitcnt lgkmcnt(0)
	v_mfma_f32_16x16x32_bf16 v[126:129], v[130:133], v[162:165], v[126:129]
	v_mfma_f32_16x16x32_bf16 v[94:97], v[138:141], v[162:165], v[94:97]
	v_mfma_f32_16x16x32_bf16 v[110:113], v[130:133], v[170:173], v[110:113]
	v_mfma_f32_16x16x32_bf16 v[70:73], v[138:141], v[170:173], v[70:73]
	v_mfma_f32_16x16x32_bf16 v[106:109], v[130:133], v[190:193], v[106:109]
	v_mfma_f32_16x16x32_bf16 v[66:69], v[138:141], v[190:193], v[66:69]
	v_mfma_f32_16x16x32_bf16 v[118:121], v[130:133], v[198:201], v[118:121]
	v_mfma_f32_16x16x32_bf16 v[86:89], v[138:141], v[198:201], v[86:89]
	v_mfma_f32_16x16x32_bf16 v[126:129], v[134:137], v[166:169], v[126:129]
	v_mfma_f32_16x16x32_bf16 v[94:97], v[142:145], v[166:169], v[94:97]
	v_mfma_f32_16x16x32_bf16 v[110:113], v[134:137], v[174:177], v[110:113]
	v_mfma_f32_16x16x32_bf16 v[70:73], v[142:145], v[174:177], v[70:73]
	v_mfma_f32_16x16x32_bf16 v[106:109], v[134:137], v[194:197], v[106:109]
	v_mfma_f32_16x16x32_bf16 v[66:69], v[142:145], v[194:197], v[66:69]
	v_mfma_f32_16x16x32_bf16 v[118:121], v[134:137], v[202:205], v[118:121]
	v_mfma_f32_16x16x32_bf16 v[86:89], v[142:145], v[202:205], v[86:89]
	s_setprio 0
	s_setprio 1
	v_mfma_f32_16x16x32_bf16 v[122:125], v[146:149], v[162:165], v[122:125]
	v_mfma_f32_16x16x32_bf16 v[90:93], v[154:157], v[162:165], v[90:93]
	v_mfma_f32_16x16x32_bf16 v[102:105], v[146:149], v[170:173], v[102:105]
	v_mfma_f32_16x16x32_bf16 v[62:65], v[154:157], v[170:173], v[62:65]
	v_mfma_f32_16x16x32_bf16 v[98:101], v[146:149], v[190:193], v[98:101]
	v_mfma_f32_16x16x32_bf16 v[58:61], v[154:157], v[190:193], v[58:61]
	v_mfma_f32_16x16x32_bf16 v[114:117], v[146:149], v[198:201], v[114:117]
	v_mfma_f32_16x16x32_bf16 v[82:85], v[154:157], v[198:201], v[82:85]
	v_mfma_f32_16x16x32_bf16 v[122:125], v[150:153], v[166:169], v[122:125]
	v_mfma_f32_16x16x32_bf16 v[90:93], v[158:161], v[166:169], v[90:93]
	v_mfma_f32_16x16x32_bf16 v[102:105], v[150:153], v[174:177], v[102:105]
	v_mfma_f32_16x16x32_bf16 v[62:65], v[158:161], v[174:177], v[62:65]
	v_mfma_f32_16x16x32_bf16 v[98:101], v[150:153], v[194:197], v[98:101]
	v_mfma_f32_16x16x32_bf16 v[58:61], v[158:161], v[194:197], v[58:61]
	v_mfma_f32_16x16x32_bf16 v[114:117], v[150:153], v[202:205], v[114:117]
	v_mfma_f32_16x16x32_bf16 v[82:85], v[158:161], v[202:205], v[82:85]
	s_setprio 0
	s_barrier
	s_mov_b32 m0, s51
	s_add_u32 s100, s14, s66
	s_addc_u32 s101, s15, s67
	s_add_u32 s14, s14, 0x80080
	s_addc_u32 s15, s15, 0
	ds_read_b128 v[162:165], v209 offset:49152
	ds_read_b128 v[166:169], v209 offset:50176
	ds_read_b128 v[170:173], v209 offset:51200
	ds_read_b128 v[174:177], v209 offset:52224
	ds_read_b128 v[190:193], v209 offset:53248
	ds_read_b128 v[194:197], v209 offset:54272
	ds_read_b128 v[198:201], v209 offset:55296
	ds_read_b128 v[202:205], v209 offset:56320
	global_load_lds_dwordx4 v180, s[100:101]
	s_mov_b32 m0, s95
	s_nop 0
	global_load_lds_dwordx4 v184, s[100:101]
	s_add_u32 s100, s46, s66
	s_addc_u32 s101, s47, s67
	s_mov_b32 m0, s50
	s_nop 0
	global_load_lds_dwordx4 v180, s[14:15]
	s_mov_b32 m0, s49
	s_nop 0
	global_load_lds_dwordx4 v184, s[14:15]
	s_mov_b32 m0, s58
	s_nop 0
	global_load_lds_dwordx4 v178, s[100:101]
	s_mov_b32 m0, s59
	s_nop 0
	global_load_lds_dwordx4 v182, s[100:101]
	s_waitcnt vmcnt(8)
	s_waitcnt lgkmcnt(0)
	s_barrier
	s_setprio 1
	s_waitcnt lgkmcnt(0)
	v_mfma_f32_16x16x32_bf16 v[46:49], v[130:133], v[162:165], v[46:49]
	v_mfma_f32_16x16x32_bf16 v[22:25], v[138:141], v[162:165], v[22:25]
	v_mfma_f32_16x16x32_bf16 v[42:45], v[130:133], v[170:173], v[42:45]
	v_mfma_f32_16x16x32_bf16 v[18:21], v[138:141], v[170:173], v[18:21]
	v_mfma_f32_16x16x32_bf16 v[38:41], v[130:133], v[190:193], v[38:41]
	v_mfma_f32_16x16x32_bf16 v[14:17], v[138:141], v[190:193], v[14:17]
	v_mfma_f32_16x16x32_bf16 v[78:81], v[130:133], v[198:201], v[78:81]
	v_mfma_f32_16x16x32_bf16 v[54:57], v[138:141], v[198:201], v[54:57]
	v_mfma_f32_16x16x32_bf16 v[46:49], v[134:137], v[166:169], v[46:49]
	v_mfma_f32_16x16x32_bf16 v[22:25], v[142:145], v[166:169], v[22:25]
	v_mfma_f32_16x16x32_bf16 v[42:45], v[134:137], v[174:177], v[42:45]
	v_mfma_f32_16x16x32_bf16 v[18:21], v[142:145], v[174:177], v[18:21]
	v_mfma_f32_16x16x32_bf16 v[38:41], v[134:137], v[194:197], v[38:41]
	v_mfma_f32_16x16x32_bf16 v[14:17], v[142:145], v[194:197], v[14:17]
	v_mfma_f32_16x16x32_bf16 v[78:81], v[134:137], v[202:205], v[78:81]
	v_mfma_f32_16x16x32_bf16 v[54:57], v[142:145], v[202:205], v[54:57]
	s_setprio 0
	s_setprio 1
	v_mfma_f32_16x16x32_bf16 v[34:37], v[146:149], v[162:165], v[34:37]
	v_mfma_f32_16x16x32_bf16 v[10:13], v[154:157], v[162:165], v[10:13]
	v_mfma_f32_16x16x32_bf16 v[30:33], v[146:149], v[170:173], v[30:33]
	v_mfma_f32_16x16x32_bf16 v[6:9], v[154:157], v[170:173], v[6:9]
	v_mfma_f32_16x16x32_bf16 v[26:29], v[146:149], v[190:193], v[26:29]
	v_mfma_f32_16x16x32_bf16 v[2:5], v[154:157], v[190:193], v[2:5]
	v_mfma_f32_16x16x32_bf16 v[74:77], v[146:149], v[198:201], v[74:77]
	v_mfma_f32_16x16x32_bf16 v[50:53], v[154:157], v[198:201], v[50:53]
	v_mfma_f32_16x16x32_bf16 v[34:37], v[150:153], v[166:169], v[34:37]
	v_mfma_f32_16x16x32_bf16 v[10:13], v[158:161], v[166:169], v[10:13]
	v_mfma_f32_16x16x32_bf16 v[30:33], v[150:153], v[174:177], v[30:33]
	v_mfma_f32_16x16x32_bf16 v[6:9], v[158:161], v[174:177], v[6:9]
	v_mfma_f32_16x16x32_bf16 v[26:29], v[150:153], v[194:197], v[26:29]
	v_mfma_f32_16x16x32_bf16 v[2:5], v[158:161], v[194:197], v[2:5]
	v_mfma_f32_16x16x32_bf16 v[74:77], v[150:153], v[202:205], v[74:77]
	v_mfma_f32_16x16x32_bf16 v[50:53], v[158:161], v[202:205], v[50:53]
	s_setprio 0
	s_barrier
	s_add_i32 vcc_lo, vcc_lo, 2
	s_add_u32 s12, s12, 0x100
	s_addc_u32 s13, s13, 0
	s_add_u32 s37, s37, 0x100
	s_addc_u32 s41, s41, 0
	s_cmp_gt_u32 vcc_lo, 29
	s_cbranch_scc0 .LBB0_1783
	s_and_b64 vcc, exec, s[24:25]
	s_cbranch_vccz .LBB0_1786
	s_barrier

; __global__ void __launch_bounds__(NWAVES * 64, 2) mk_fwd(Args args) {
	.amdhsa_kernel _Z6mk_fwd4Args
		.amdhsa_group_segment_fixed_size 0
		.amdhsa_private_segment_fixed_size 0
		.amdhsa_kernarg_size 496
		.amdhsa_user_sgpr_count 2
		.amdhsa_user_sgpr_dispatch_ptr 0
		.amdhsa_user_sgpr_queue_ptr 0
		.amdhsa_user_sgpr_kernarg_segment_ptr 1
		.amdhsa_user_sgpr_dispatch_id 0
		.amdhsa_user_sgpr_kernarg_preload_length 0
		.amdhsa_user_sgpr_kernarg_preload_offset 0
		.amdhsa_user_sgpr_private_segment_size 0
		.amdhsa_uses_dynamic_stack 0
		.amdhsa_enable_private_segment 0
		.amdhsa_system_sgpr_workgroup_id_x 1
		.amdhsa_system_sgpr_workgroup_id_y 0
		.amdhsa_system_sgpr_workgroup_id_z 0
		.amdhsa_system_sgpr_workgroup_info 0
		.amdhsa_system_vgpr_workitem_id 0
		.amdhsa_next_free_vgpr 256
		.amdhsa_next_free_sgpr 102
		.amdhsa_accum_offset 256
		.amdhsa_reserve_vcc 1
		.amdhsa_float_round_mode_32 0
		.amdhsa_float_round_mode_16_64 0
		.amdhsa_float_denorm_mode_32 3
		.amdhsa_float_denorm_mode_16_64 3
		.amdhsa_dx10_clamp 1
		.amdhsa_ieee_mode 1
		.amdhsa_fp16_overflow 0
		.amdhsa_tg_split 0
		.amdhsa_exception_fp_ieee_invalid_op 0
		.amdhsa_exception_fp_denorm_src 0
		.amdhsa_exception_fp_ieee_div_zero 0
		.amdhsa_exception_fp_ieee_overflow 0
		.amdhsa_exception_fp_ieee_underflow 0
		.amdhsa_exception_fp_ieee_inexact 0
		.amdhsa_exception_int_div_zero 0
	.end_amdhsa_kernel

; __global__ void __launch_bounds__(NWAVES * 64, 2) mk_fwd(Args args) {
amdhsa.kernels:
  - .agpr_count:     0
    .args:
      - .offset:         0
        .size:           240
        .value_kind:     by_value
      - .offset:         240
        .size:           4
        .value_kind:     hidden_block_count_x
      - .offset:         244
        .size:           4
        .value_kind:     hidden_block_count_y
      - .offset:         248
        .size:           4
        .value_kind:     hidden_block_count_z
      - .offset:         252
        .size:           2
        .value_kind:     hidden_group_size_x
      - .offset:         254
        .size:           2
        .value_kind:     hidden_group_size_y
      - .offset:         256
        .size:           2
        .value_kind:     hidden_group_size_z
      - .offset:         258
        .size:           2
        .value_kind:     hidden_remainder_x
      - .offset:         260
        .size:           2
        .value_kind:     hidden_remainder_y
      - .offset:         262
        .size:           2
        .value_kind:     hidden_remainder_z
      - .offset:         280
        .size:           8
        .value_kind:     hidden_global_offset_x
      - .offset:         288
        .size:           8
        .value_kind:     hidden_global_offset_y
      - .offset:         296
        .size:           8
        .value_kind:     hidden_global_offset_z
      - .offset:         304
        .size:           2
        .value_kind:     hidden_grid_dims
      - .offset:         360
        .size:           4
        .value_kind:     hidden_dynamic_lds_size
    .group_segment_fixed_size: 0
    .kernarg_segment_align: 8
    .kernarg_segment_size: 496
    .language:       OpenCL C
    .language_version:
      - 2
      - 0
    .max_flat_workgroup_size: 512
    .name:           _Z6mk_fwd4Args
    .private_segment_fixed_size: 0
    .sgpr_count:     108
    .sgpr_spill_count: 95
    .symbol:         _Z6mk_fwd4Args.kd
    .uniform_work_group_size: 1
    .uses_dynamic_stack: false
    .vgpr_count:     256
    .vgpr_spill_count: 0
    .wavefront_size: 64
